# post-norm row loop: next-layer gains loaded once before the loop (no per-row vmcnt(0) drains), in-loop waits no longer wait for previous row store acks
# speedup vs baseline: 1.0063x; 1.0063x over previous
.LBB0_34:
	v_lshlrev_b32_e32 v4, 3, v18
	v_and_b32_e32 v20, 0x1f8, v4
	v_lshlrev_b64 v[2:3], 12, v[2:3]
	v_readlane_b32 s2, v255, 0
	v_lshlrev_b32_e32 v22, 2, v20
	v_mov_b32_e32 v23, v177
	v_lshl_add_u64 v[0:1], v[0:1], 0, v[2:3]
	s_cmp_lg_u32 s2, 1
	v_lshl_add_u64 v[0:1], v[0:1], 0, v[22:23]
	v_readlane_b32 s3, v255, 1
	s_cselect_b64 s[8:9], -1, 0
	global_load_dwordx4 v[40:43], v[0:1], off offset:2064
	global_load_dwordx4 v[44:47], v[0:1], off offset:2048
	global_load_dwordx4 v[48:51], v[0:1], off offset:16
	global_load_dwordx4 v[52:55], v[0:1], off
	v_lshlrev_b64 v[0:1], 11, v[64:65]
	s_lshl_b32 s2, s2, 10
	v_lshlrev_b32_e32 v176, 1, v20
	s_waitcnt lgkmcnt(0)
	v_lshl_add_u64 v[4:5], s[82:83], 0, v[22:23]
	v_lshl_add_u64 v[0:1], s[70:71], 0, v[0:1]
	s_ashr_i32 s3, s2, 31
	v_lshl_add_u64 v[0:1], v[0:1], 0, v[176:177]
	v_lshl_add_u64 v[12:13], s[2:3], 2, v[4:5]
	global_load_dwordx4 v[56:59], v[0:1], off offset:1024
	global_load_dwordx4 v[60:63], v[0:1], off
	s_nop 0
	global_load_dwordx4 v[0:3], v[12:13], off
	global_load_dwordx4 v[4:7], v[12:13], off offset:16
	global_load_dwordx4 v[8:11], v[12:13], off offset:2048
	s_nop 0
	global_load_dwordx4 v[12:15], v[12:13], off offset:2064
	s_addk_i32 s2, 0x400
	v_lshl_add_u64 v[22:23], s[80:81], 0, v[22:23]
	s_ashr_i32 s3, s2, 31
	v_lshl_add_u64 v[68:69], s[2:3], 2, v[22:23]
	v_readlane_b32 s2, v254, 44
	v_ashrrev_i32_e32 v17, 31, v16
	v_readlane_b32 s3, v254, 45
	v_and_b32_e32 v18, 63, v18
	v_lshl_add_u64 v[66:67], s[70:71], 0, v[176:177]
	v_lshl_add_u64 v[16:17], s[2:3], 0, v[16:17]
	v_lshlrev_b64 v[70:71], 12, v[16:17]
	v_lshlrev_b64 v[16:17], 11, v[16:17]
	v_readlane_b32 s2, v254, 48
	v_lshl_or_b32 v16, v18, 4, v16
	v_readlane_b32 s3, v254, 49
	v_lshl_or_b32 v70, v18, 5, v70
	s_mov_b64 s[10:11], 0
	v_lshl_add_u64 v[72:73], s[2:3], 0, v[16:17]
	v_lshlrev_b32_e32 v74, 2, v20
	v_mov_b32_e32 v75, v177
	s_and_b64 vcc, exec, s[8:9]
	s_cbranch_vccz .Lpn_skip
	global_load_dwordx4 v[100:103], v[68:69], off
	global_load_dwordx4 v[104:107], v[68:69], off offset:16
	global_load_dwordx4 v[108:111], v[68:69], off offset:2048
	global_load_dwordx4 v[112:115], v[68:69], off offset:2064
.Lpn_skip:
	s_waitcnt vmcnt(0)
	s_branch .LBB0_36

.LBB0_44:
	v_lshlrev_b64 v[20:21], 12, v[20:21]
	v_lshl_add_u64 v[24:25], v[18:19], 0, v[20:21]
	v_lshlrev_b64 v[16:17], 11, v[16:17]
	v_lshl_add_u64 v[20:21], v[66:67], 0, v[16:17]
	v_lshl_add_u64 v[32:33], v[24:25], 0, v[74:75]
	global_load_dwordx4 v[16:19], v[20:21], off
	s_nop 0
	global_load_dwordx4 v[20:23], v[20:21], off offset:1024
	s_nop 0
	global_load_dwordx4 v[28:31], v[32:33], off offset:16
	global_load_dwordx4 v[36:39], v[32:33], off
	global_load_dwordx4 v[24:27], v[32:33], off offset:2064
	s_nop 0
	global_load_dwordx4 v[32:35], v[32:33], off offset:2048
	s_waitcnt vmcnt(10)
	v_lshlrev_b32_e32 v86, 16, v60
	v_and_b32_e32 v87, 0xffff0000, v60
	v_lshlrev_b32_e32 v82, 16, v61
	v_and_b32_e32 v83, 0xffff0000, v61
	v_mul_f32_e32 v60, v86, v86
	v_mul_f32_e32 v61, v87, v87
	v_mul_f32_e32 v84, v82, v82
	v_mul_f32_e32 v85, v83, v83
	v_add_f32_e32 v60, v60, v61
	v_lshlrev_b32_e32 v80, 16, v62
	v_and_b32_e32 v81, 0xffff0000, v62
	v_add_f32_e32 v60, v84, v60
	v_lshlrev_b32_e32 v76, 16, v63
	v_and_b32_e32 v77, 0xffff0000, v63
	v_mul_f32_e32 v62, v80, v80
	v_mul_f32_e32 v63, v81, v81
	v_add_f32_e32 v60, v85, v60
	v_add_f32_e32 v60, v62, v60
	v_mul_f32_e32 v78, v76, v76
	v_mul_f32_e32 v79, v77, v77
	v_add_f32_e32 v60, v63, v60
	v_lshlrev_b32_e32 v98, 16, v56
	v_and_b32_e32 v99, 0xffff0000, v56
	v_add_f32_e32 v60, v78, v60
	v_lshlrev_b32_e32 v94, 16, v57
	v_and_b32_e32 v95, 0xffff0000, v57
	v_mul_f32_e32 v56, v98, v98
	v_mul_f32_e32 v57, v99, v99
	v_add_f32_e32 v60, v79, v60
	v_add_f32_e32 v56, v56, v60
	v_mul_f32_e32 v96, v94, v94
	v_mul_f32_e32 v97, v95, v95
	v_add_f32_e32 v56, v57, v56
	v_lshlrev_b32_e32 v92, 16, v58
	v_and_b32_e32 v93, 0xffff0000, v58
	v_add_f32_e32 v56, v96, v56
	v_lshlrev_b32_e32 v88, 16, v59
	v_and_b32_e32 v89, 0xffff0000, v59
	v_mul_f32_e32 v58, v92, v92
	v_mul_f32_e32 v59, v93, v93
	v_add_f32_e32 v56, v97, v56
	v_add_f32_e32 v56, v58, v56
	v_mul_f32_e32 v90, v88, v88
	v_mul_f32_e32 v91, v89, v89
	v_add_f32_e32 v56, v59, v56
	v_add_f32_e32 v56, v90, v56
	v_add_f32_e32 v56, v91, v56
	s_nop 1
	v_add_f32_dpp v56, v56, v56 quad_perm:[1,0,3,2] row_mask:0xf bank_mask:0xf bound_ctrl:1
	s_nop 1
	v_add_f32_dpp v56, v56, v56 quad_perm:[2,3,0,1] row_mask:0xf bank_mask:0xf bound_ctrl:1
	s_nop 1
	v_add_f32_dpp v56, v56, v56 row_half_mirror row_mask:0xf bank_mask:0xf bound_ctrl:1
	s_nop 1
	v_add_f32_dpp v56, v56, v56 row_mirror row_mask:0xf bank_mask:0xf bound_ctrl:1
	v_mov_b32_e32 v57, v56
	s_nop 1
	v_permlane16_swap_b32_e32 v56, v57
	v_add_f32_e32 v56, v56, v57
	v_mov_b32_e32 v57, v56
	s_nop 1
	v_permlane32_swap_b32_e32 v56, v57
	v_add_f32_e32 v56, v56, v57
	v_fmamk_f32 v56, v56, 0x3a800000, v230
	v_mul_f32_e32 v57, 0x4b800000, v56
	v_cmp_gt_f32_e32 vcc, s91, v56
	s_nop 1
	v_cndmask_b32_e32 v56, v56, v57, vcc
	v_rsq_f32_e32 v56, v56
	s_nop 0
	v_mul_f32_e32 v57, 0x45800000, v56
	v_cndmask_b32_e32 v56, v56, v57, vcc
	v_mul_f32_e32 v58, v56, v86
	v_mul_f32_e32 v59, v56, v87
	s_nop 0
	v_fma_f32 v52, v0, v58, v52
	v_fma_f32 v53, v1, v59, v53
	v_mul_f32_e32 v58, v56, v80
	v_mul_f32_e32 v59, v56, v81
	s_nop 0
	v_fma_f32 v48, v4, v58, v48
	v_fma_f32 v49, v5, v59, v49
	v_mul_f32_e32 v58, v56, v82
	v_mul_f32_e32 v59, v56, v83
	v_fma_f32 v54, v2, v58, v54
	v_fma_f32 v55, v3, v59, v55
	v_mul_f32_e32 v58, v56, v76
	v_mul_f32_e32 v59, v56, v77
	v_fma_f32 v50, v6, v58, v50
	v_fma_f32 v51, v7, v59, v51
	v_mul_f32_e32 v58, v56, v98
	v_mul_f32_e32 v59, v56, v99
	s_nop 0
	v_fma_f32 v44, v8, v58, v44
	v_fma_f32 v45, v9, v59, v45
	v_mul_f32_e32 v58, v56, v92
	v_mul_f32_e32 v59, v56, v93
	s_nop 0
	v_fma_f32 v40, v12, v58, v40
	v_fma_f32 v41, v13, v59, v41
	v_mul_f32_e32 v58, v56, v94
	v_mul_f32_e32 v59, v56, v95
	v_mul_f32_e32 v57, v56, v89
	v_mul_f32_e32 v56, v56, v88
	v_fma_f32 v46, v10, v58, v46
	v_fma_f32 v47, v11, v59, v47
	v_fma_f32 v42, v14, v56, v42
	v_fma_f32 v43, v15, v57, v43
	v_lshl_add_u64 v[56:57], s[68:69], 0, v[70:71]
	s_andn2_b64 vcc, exec, s[8:9]
	global_store_dwordx4 v[56:57], v[52:55], off
	global_store_dwordx4 v[56:57], v[48:51], off offset:16
	global_store_dwordx4 v[56:57], v[44:47], off offset:2048
	global_store_dwordx4 v[56:57], v[40:43], off offset:2064
	s_cbranch_vccnz .LBB0_35
	v_mul_f32_e32 v56, v52, v52
	v_mul_f32_e32 v57, v53, v53
	v_mul_f32_e32 v58, v54, v54
	v_mul_f32_e32 v59, v55, v55
	v_add_f32_e32 v56, v56, v57
	v_add_f32_e32 v56, v58, v56
	v_mul_f32_e32 v60, v48, v48
	v_mul_f32_e32 v61, v49, v49
	v_add_f32_e32 v56, v59, v56
	v_add_f32_e32 v56, v60, v56
	v_mul_f32_e32 v62, v50, v50
	v_mul_f32_e32 v63, v51, v51
	v_add_f32_e32 v56, v61, v56
	v_add_f32_e32 v56, v62, v56
	v_mul_f32_e32 v76, v44, v44
	v_mul_f32_e32 v77, v45, v45
	v_add_f32_e32 v56, v63, v56
	v_add_f32_e32 v56, v76, v56
	v_mul_f32_e32 v78, v46, v46
	v_mul_f32_e32 v79, v47, v47
	v_add_f32_e32 v56, v77, v56
	v_add_f32_e32 v56, v78, v56
	v_mul_f32_e32 v80, v40, v40
	v_mul_f32_e32 v81, v41, v41
	v_add_f32_e32 v56, v79, v56
	v_add_f32_e32 v56, v80, v56
	v_mul_f32_e32 v82, v42, v42
	v_mul_f32_e32 v83, v43, v43
	v_add_f32_e32 v56, v81, v56
	v_add_f32_e32 v56, v82, v56
	v_add_f32_e32 v56, v83, v56
	s_nop 1
	v_add_f32_dpp v56, v56, v56 quad_perm:[1,0,3,2] row_mask:0xf bank_mask:0xf bound_ctrl:1
	s_nop 1
	v_add_f32_dpp v56, v56, v56 quad_perm:[2,3,0,1] row_mask:0xf bank_mask:0xf bound_ctrl:1
	s_nop 1
	v_add_f32_dpp v56, v56, v56 row_half_mirror row_mask:0xf bank_mask:0xf bound_ctrl:1
	s_nop 1
	v_add_f32_dpp v56, v56, v56 row_mirror row_mask:0xf bank_mask:0xf bound_ctrl:1
	v_mov_b32_e32 v57, v56
	s_nop 1
	v_permlane16_swap_b32_e32 v56, v57
	v_add_f32_e32 v56, v56, v57
	v_mov_b32_e32 v57, v56
	s_nop 1
	v_permlane32_swap_b32_e32 v56, v57
	v_add_f32_e32 v56, v56, v57
	v_fmamk_f32 v56, v56, 0x3a800000, v230
	v_cmp_gt_f32_e32 vcc, s91, v56
	v_mul_f32_e32 v57, 0x4b800000, v56
	s_nop 0
	v_cndmask_b32_e32 v56, v56, v57, vcc
	v_rsq_f32_e32 v56, v56
	s_nop 0
	v_mul_f32_e32 v57, 0x45800000, v56
	v_cndmask_b32_e32 v60, v56, v57, vcc
	s_nop 0
	s_nop 0
	v_mul_f32_e32 v52, v52, v60
	v_mul_f32_e32 v53, v53, v60
	v_mul_f32_e32 v54, v54, v60
	v_mul_f32_e32 v55, v55, v60
	v_mul_f32_e32 v48, v48, v60
	v_mul_f32_e32 v49, v49, v60
	v_mul_f32_e32 v44, v44, v60
	v_mul_f32_e32 v45, v45, v60
	v_mul_f32_e32 v46, v46, v60
	v_mul_f32_e32 v47, v47, v60
	v_mul_f32_e32 v40, v40, v60
	v_mul_f32_e32 v41, v41, v60
	s_nop 0
	v_mul_f32_e32 v48, v104, v48
	v_mul_f32_e32 v49, v105, v49
	s_nop 0
	v_mul_f32_e32 v52, v100, v52
	v_mul_f32_e32 v53, v101, v53
	v_mul_f32_e32 v54, v102, v54
	v_mul_f32_e32 v55, v103, v55
	v_cvt_pk_bf16_f32 v52, v52, v53
	v_cvt_pk_bf16_f32 v53, v54, v55
	v_cvt_pk_bf16_f32 v54, v48, v49
	v_mul_f32_e32 v48, v50, v60
	v_mul_f32_e32 v49, v51, v60
	s_nop 0
	v_mul_f32_e32 v48, v106, v48
	v_mul_f32_e32 v49, v107, v49
	s_nop 0
	v_cvt_pk_bf16_f32 v55, v48, v49
	global_store_dwordx4 v[72:73], v[52:55], off offset:-1024
	s_nop 0
	s_nop 0
	s_nop 0
	s_nop 0
	v_mul_f32_e32 v40, v112, v40
	v_mul_f32_e32 v41, v113, v41
	s_nop 0
	v_mul_f32_e32 v44, v108, v44
	v_mul_f32_e32 v45, v109, v45
	v_mul_f32_e32 v46, v110, v46
	v_mul_f32_e32 v47, v111, v47
	v_cvt_pk_bf16_f32 v44, v44, v45
	v_cvt_pk_bf16_f32 v45, v46, v47
	v_cvt_pk_bf16_f32 v46, v40, v41
	v_mul_f32_e32 v40, v42, v60
	v_mul_f32_e32 v41, v43, v60
	s_nop 0
	v_mul_f32_e32 v40, v114, v40
	v_mul_f32_e32 v41, v115, v41
	s_nop 0
	v_cvt_pk_bf16_f32 v47, v40, v41
	global_store_dwordx4 v[72:73], v[44:47], off
	s_branch .LBB0_35
